# attention half 2: fp8 pack ops rebalanced across the last two QK MFMA gaps
# baseline (speedup 1.0000x reference)
; #define LAS __attribute__((address_space(3)))
; template <bool FIRST>
; __device__ __forceinline__ void partialSM(f32x16& p0, f32x16& p1, f32x16& negm, float& dl, float& alpha) {
;     float pmax = p0[0];
; #pragma unroll
;     for (int r = 1; r < 16; ++r) pmax = fmaxf(pmax, p0[r]);
; #pragma unroll
;     for (int r = 0; r < 16; ++r) pmax = fmaxf(pmax, p1[r]);
;     { auto rr = __builtin_amdgcn_permlane32_swap(__float_as_uint(pmax), __float_as_uint(pmax), false, false);
;       pmax = fmaxf(__uint_as_float(rr[0]), __uint_as_float(rr[1])); }
;     if (FIRST) {
;         dl = 0.f; alpha = 1.f; const float d0_ = pmax - SH;
; #pragma unroll
;         for (int r = 0; r < 16; ++r) { p0[r] -= d0_; p1[r] -= d0_; negm[r] -= d0_; }
;     } else {
;         const bool keep = __all(pmax <= SH + THRL);
;         dl = keep ? 0.f : fmaxf(pmax - SH, 0.f); alpha = __builtin_amdgcn_exp2f(-dl);
;     }
; #pragma unroll
;     for (int r = 0; r < 16; ++r) p0[r] = __builtin_amdgcn_exp2f(p0[r]);
; }
; __device__ __forceinline__ void finishSM(f32x16& p0, f32x16& p1, v8i& pa) {
; #pragma unroll
;     for (int r = 0; r < 16; ++r) p1[r] = __builtin_amdgcn_exp2f(p1[r]);
; #pragma unroll
;     for (int w = 0; w < 4; ++w) { pa[w] = (int)pk4_fp8(p0[4 * w], p0[4 * w + 1], p0[4 * w + 2], p0[4 * w + 3]); pa[4 + w] = (int)pk4_fp8(p1[4 * w], p1[4 * w + 1], p1[4 * w + 2], p1[4 * w + 3]); }
; }
; __device__ __forceinline__ v8i ld32(const LAS char* a0, const LAS char* a1) { const v4i x = *(const LAS v4i*)a0, y = *(const LAS v4i*)a1; return (v8i){x[0], x[1], x[2], x[3], y[0], y[1], y[2], y[3]}; }
; __device__ __forceinline__ void qkt(f32x16& p0, f32x16& p1, const LAS char* Ks, int ka0, int ka1, const v8i* qf, const f32x16& negm) {
; #pragma unroll
;     for (int st = 0; st < 3; ++st) {
;         const v8i k0 = ld32(Ks + ka0 + 64 * st, Ks + ka1 + 64 * st), k1 = ld32(Ks + ka0 + 64 * st + 32 * 192, Ks + ka1 + 64 * st + 32 * 192);
;         if (st == 0) { p0 = MFMA8QK(k0, qf[st], negm); p1 = MFMA8QK(k1, qf[st], negm); }
;         else { p0 = MFMA8QK(k0, qf[st], p0); p1 = MFMA8QK(k1, qf[st], p1); } }
; }
; __device__ __forceinline__ void pv_d0(f32x16* o, const LAS char* Vs, int va0, int va1, v8i pa) {
; #pragma unroll
;     for (int d0 = 0; d0 < 4; ++d0) { const v8i vf = ld32(Vs + va0 + 2048 * d0, Vs + va1 + 2048 * d0); o[d0] = MFMA8(pa, vf, o[d0]); }
.LBB0_615:
	s_mul_hi_u32 s0, s15, 0xaaaaaaab
	s_lshr_b32 s0, s0, 1
	s_mul_i32 s0, s0, 0xffff4000
	s_bfe_i32 s1, s21, 0x10001
	s_and_b32 s1, s1, 0x6000
	s_add_i32 s1, s1, 0
	v_add_u32_e32 v0, s1, v244
	v_add_u32_e32 v161, s1, v245
	ds_read_b128 v[194:197], v0 offset:55360
	ds_read_b128 v[198:201], v161 offset:55360
	v_exp_f32_e32 v129, v129
	v_exp_f32_e32 v162, v133
	s_waitcnt lgkmcnt(4)
	v_mfma_scale_f32_32x32x64_f8f6f4 v[144:159], v[208:215], v[184:191], v[96:111], v234, v233 op_sel_hi:[0,0,0]
	ds_read_b128 v[202:205], v0 offset:49216
	ds_read_b128 v[206:209], v161 offset:49216
	v_exp_f32_e32 v130, v130
	v_exp_f32_e32 v131, v131
	v_exp_f32_e32 v134, v134
	v_exp_f32_e32 v135, v135
	s_waitcnt lgkmcnt(4)
	v_mfma_scale_f32_32x32x64_f8f6f4 v[112:127], v[120:127], v[184:191], v[96:111], v234, v233 op_sel_hi:[0,0,0]
	v_exp_f32_e32 v136, v136
	v_exp_f32_e32 v137, v137
	v_exp_f32_e32 v140, v140
	v_exp_f32_e32 v141, v141
	s_waitcnt lgkmcnt(2)
	v_mfma_scale_f32_32x32x64_f8f6f4 v[112:127], v[194:201], v[176:183], v[112:127], v234, v233 op_sel_hi:[0,0,0]
	v_exp_f32_e32 v138, v138
	v_exp_f32_e32 v139, v139
	v_exp_f32_e32 v142, v142
	v_exp_f32_e32 v143, v143
	s_waitcnt lgkmcnt(0)
	v_mfma_scale_f32_32x32x64_f8f6f4 v[144:159], v[202:209], v[176:183], v[144:159], v234, v233 op_sel_hi:[0,0,0]
	ds_read_b128 v[194:197], v0 offset:55424
	ds_read_b128 v[198:201], v161 offset:55424
	ds_read_b128 v[202:205], v0 offset:49280
	ds_read_b128 v[206:209], v161 offset:49280
	v_exp_f32_e32 v0, v128
	v_exp_f32_e32 v161, v132
	v_cvt_pk_fp8_f32 v132, v0, v129
	v_cvt_pk_fp8_f32 v133, v161, v162
	v_cvt_pk_fp8_f32 v128, v14, v15
	v_cvt_pk_fp8_f32 v132, v130, v131 op_sel:[0,0,1]
	v_cvt_pk_fp8_f32 v133, v134, v135 op_sel:[0,0,1]
	v_cvt_pk_fp8_f32 v129, v10, v11
	v_cvt_pk_fp8_f32 v130, v6, v7
	v_cvt_pk_fp8_f32 v134, v136, v137
	s_waitcnt lgkmcnt(0)
	v_mfma_scale_f32_32x32x64_f8f6f4 v[112:127], v[194:201], v[168:175], v[112:127], v234, v233 op_sel_hi:[0,0,0]
	v_cvt_pk_fp8_f32 v131, v2, v3
	v_cvt_pk_fp8_f32 v135, v140, v141
	v_cvt_pk_fp8_f32 v128, v192, v193 op_sel:[0,0,1]
	v_cvt_pk_fp8_f32 v129, v12, v13 op_sel:[0,0,1]
	v_cvt_pk_fp8_f32 v130, v8, v9 op_sel:[0,0,1]
	v_cvt_pk_fp8_f32 v134, v138, v139 op_sel:[0,0,1]
	v_cvt_pk_fp8_f32 v131, v4, v5 op_sel:[0,0,1]
	v_cvt_pk_fp8_f32 v135, v142, v143 op_sel:[0,0,1]
	v_or_b32_e32 v10, s0, v218
	v_or_b32_e32 v11, s0, v250
	v_add_u32_e32 v10, v247, v10
	v_add_u32_e32 v11, v247, v11
	ds_read_b128 v[2:5], v10
	ds_read_b128 v[6:9], v11
	v_mfma_scale_f32_32x32x64_f8f6f4 v[144:159], v[202:209], v[168:175], v[144:159], v234, v233 op_sel_hi:[0,0,0]
	ds_read_b128 v[194:197], v10 offset:2048
	ds_read_b128 v[198:201], v11 offset:2048
	v_mov_b32_e32 v161, v160
	v_mov_b32_e32 v162, v160
	v_mov_b32_e32 v163, v160
	v_mov_b32_e32 v164, v160
	v_mov_b32_e32 v165, v160
	v_mov_b32_e32 v166, v160
	v_mov_b32_e32 v167, v160
	s_waitcnt lgkmcnt(2)
	v_mfma_scale_f32_32x32x64_f8f6f4 v[64:79], v[128:135], v[2:9], v[64:79], v234, v234 op_sel_hi:[0,0,0]
	ds_read_b128 v[2:5], v10 offset:4096
	ds_read_b128 v[6:9], v11 offset:4096
	s_waitcnt lgkmcnt(2)
	v_mfma_scale_f32_32x32x64_f8f6f4 v[48:63], v[128:135], v[194:201], v[48:63], v234, v234 op_sel_hi:[0,0,0]
	ds_read_b128 v[194:197], v10 offset:6144
	ds_read_b128 v[198:201], v11 offset:6144
	s_nop 2
	v_exp_f32_e32 v228, v144
	v_exp_f32_e32 v229, v145
	v_exp_f32_e32 v220, v146
	v_exp_f32_e32 v221, v147
	v_exp_f32_e32 v226, v148
	s_waitcnt lgkmcnt(2)
	v_mfma_scale_f32_32x32x64_f8f6f4 v[32:47], v[128:135], v[2:9], v[32:47], v234, v234 op_sel_hi:[0,0,0]
	v_exp_f32_e32 v227, v149
	v_exp_f32_e32 v224, v150
	v_exp_f32_e32 v225, v151
	v_exp_f32_e32 v222, v152
	v_exp_f32_e32 v223, v153
	v_max_f32_e32 v0, v144, v145
	v_max3_f32 v0, v0, v146, v147
	v_max3_f32 v0, v0, v148, v149
	v_max3_f32 v0, v0, v150, v151
	v_max3_f32 v0, v0, v152, v153
	s_waitcnt lgkmcnt(0)
	v_mfma_scale_f32_32x32x64_f8f6f4 v[16:31], v[128:135], v[194:201], v[16:31], v234, v234 op_sel_hi:[0,0,0]
	s_bitcmp0_b32 s15, 0
	s_cselect_b32 s1, 0x6000, 0
	v_add_u32_e32 v12, s1, v244
	v_add_u32_e32 v13, s1, v245
	v_add_u32_e32 v14, 0xf000, v12
	v_add_u32_e32 v15, 0xf000, v13
	ds_read_b128 v[202:205], v12 offset:61440
	ds_read_b128 v[206:209], v13 offset:61440
	ds_read_b128 v[194:197], v14 offset:6144
	ds_read_b128 v[198:201], v15 offset:6144
	v_max3_f32 v0, v0, v154, v155
	v_max3_f32 v0, v0, v156, v157
	v_max3_f32 v0, v0, v158, v159
	v_max3_f32 v0, v0, v112, v113
	v_max3_f32 v0, v0, v114, v115
	v_max3_f32 v0, v0, v116, v117
	v_max3_f32 v0, v0, v118, v119
	v_max3_f32 v0, v0, v120, v121
	v_max3_f32 v0, v0, v122, v123
	v_mfma_scale_f32_32x32x64_f8f6f4 v[80:95], v[128:135], v[160:167], v[80:95], v234, v234 op_sel_hi:[0,0,0]
	v_max3_f32 v0, v0, v124, v125
	v_max3_f32 v0, v0, v126, v127
	v_mov_b32_e32 v2, v0
	s_nop 1
	v_permlane32_swap_b32_e32 v0, v2
	v_max_f32_e32 v0, v0, v2
	v_cmp_ge_f32_e32 vcc, s67, v0
	v_exp_f32_e32 v162, v154
	s_cmp_lg_u64 vcc, exec
	v_exp_f32_e32 v163, v155
	v_exp_f32_e32 v166, v156
	v_exp_f32_e32 v167, v157
	v_exp_f32_e32 v164, v158
	v_exp_f32_e32 v165, v159
	s_cbranch_scc0 .LBB0_588
	v_add_f32_e32 v2, -4.0, v0
	v_max_f32_e32 v2, 0, v2
	v_exp_f32_e64 v0, -v2
	s_and_saveexec_b64 s[0:1], s[12:13]
	s_cbranch_execz .LBB0_587
	ds_write_b32 v243, v0 offset:128
	s_branch .LBB0_587
